# layer-0 weight conversion rebalanced against the modulation units (96 mod blocks convert 6 tiles, the rest take one extra)
# baseline (speedup 1.0000x reference)
; __device__ void ph_convert(const Params& p, int l, char* smem) {
;     ...
;   for (int t = blockIdx.x; t < 5152; t += gridDim.x) {
;     const float* src; long sld; u16* dst; int n0, k0, kind; long ntot = D;
;     if (t < 4128) { kind = 0; ntot = NPAD; n0 = (t / 16) * 64; k0 = (t % 16) * 64; src = p.w_in + (long)l * D * IN_DIM; sld = IN_DIM; dst = p.WinT; }
;     else if (t < 4896) { int u = t - 4128; int i = u / 256; u %= 256; kind = 1; n0 = (u / 16) * 64; k0 = (u % 16) * 64;
;       src = p.w_branch + ((long)l * 3 + i) * D * D; sld = D; dst = p.WbrT + (long)i * D * D; }
;     else { int u = t - 4896; kind = 1; n0 = (u / 16) * 64; k0 = (u % 16) * 64; src = p.w_out + (long)l * D * D; sld = D; dst = p.WoT; }
; #pragma unroll 4
;     for (int i = 0; i < 16; ++i) {
;       int kk = (tid >> 6) + 4 * i, nn = tid & 63;
;       int np = n0 + nn;
;       int ns = kind == 0 ? win_src_col(np) : np;
;       tile[kk][nn] = ns >= 0 ? src[(long)(k0 + kk) * sld + ns] : 0.f;
;     }
.LBB0_35:
	v_readlane_b32 s38, v242, 13
	v_readlane_b32 s39, v242, 14
	v_mov_b32_e32 v0, v156
	s_andn2_b64 vcc, exec, s[38:39]
	s_cbranch_vccnz .LBB0_59
	v_readlane_b32 s10, v241, 59
	s_mul_i32 s92, s10, 0x100c000
	v_readlane_b32 s44, v241, 9
	s_lshl_b32 s38, s10, 20
	s_lshl_b64 s[40:41], s[92:93], 2
	v_readlane_b32 s46, v241, 11
	v_readlane_b32 s45, v241, 10
	v_readlane_b32 s47, v241, 12
	s_add_u32 s42, s46, s40
	s_mov_b32 s39, s93
	s_addc_u32 s43, s47, s41
	v_readlane_b32 s44, v240, 10
	s_lshl_b64 s[38:39], s[38:39], 2
	v_readlane_b32 s46, v240, 12
	v_readlane_b32 s45, v240, 11
	v_readlane_b32 s47, v240, 13
	s_add_u32 s44, s46, s38
	s_addc_u32 s45, s47, s39
	v_and_b32_e32 v253, 63, v156
	v_lshlrev_b32_e32 v252, 4, v156
	v_lshrrev_b32_e32 v0, 6, v156
	v_mul_u32_u24_e32 v26, 0x104, v0
	v_lshl_add_u32 v26, v253, 2, v26
	v_and_b32_e32 v0, 3, v156
	v_mul_u32_u24_e32 v243, 0x820, v0
	v_lshrrev_b32_e32 v0, 2, v156
	v_lshl_add_u32 v243, v0, 2, v243
	v_readlane_b32 s54, v242, 2
	s_movk_i32 s99, 0x1420
	s_mov_b32 s98, -1
	v_readlane_b32 s38, v241, 59
	v_readlane_b32 s39, v242, 3
	s_cmp_lg_u32 s38, 0
	s_cbranch_scc1 .Lcv_setup_done
	s_cmpk_lg_u32 s39, 0x200
	s_cbranch_scc1 .Lcv_setup_done
	s_cmpk_lt_u32 s54, 0x60
	s_cbranch_scc0 .Lcv_big
	s_movk_i32 s99, 0xc00
	s_branch .Lcv_setup_done
.Lcv_big:
	s_sub_u32 s38, s54, 0x60
	s_cmpk_lt_u32 s38, 0x180
	s_cbranch_scc0 .Lcv_tailx
	s_mul_hi_u32 s39, s38, 0x2aaaaab
	s_mul_i32 s40, s39, 0x60
	s_sub_u32 s38, s38, s40
	s_add_u32 s39, s39, 6
	s_lshl_b32 s39, s39, 9
	s_add_u32 s98, s38, s39
	s_branch .Lcv_setup_done
.Lcv_tailx:
	s_add_u32 s98, s38, 0x1280
.Lcv_setup_done:
.Lcv_top:
	s_cmp_lt_i32 s54, s99
	s_cbranch_scc0 .Lcv_noload

; __device__ __forceinline__ u16 f2bf(float f) { return (u16)(pack2(f, 0.f) & 0xffffu); }
; __device__ void ph_convert(const Params& p, int l, char* smem) {
;     ...
;   for (int t = blockIdx.x; t < 5152; t += gridDim.x) {
;     const float* src; long sld; u16* dst; int n0, k0, kind; long ntot = D;
;     if (t < 4128) { kind = 0; ntot = NPAD; n0 = (t / 16) * 64; k0 = (t % 16) * 64; src = p.w_in + (long)l * D * IN_DIM; sld = IN_DIM; dst = p.WinT; }
;     else if (t < 4896) { int u = t - 4128; int i = u / 256; u %= 256; kind = 1; n0 = (u / 16) * 64; k0 = (u % 16) * 64;
;       src = p.w_branch + ((long)l * 3 + i) * D * D; sld = D; dst = p.WbrT + (long)i * D * D; }
;     else { int u = t - 4896; kind = 1; n0 = (u / 16) * 64; k0 = (u % 16) * 64; src = p.w_out + (long)l * D * D; sld = D; dst = p.WoT; }
; #pragma unroll 4
;     for (int i = 0; i < 16; ++i) {
;       int kk = (tid >> 6) + 4 * i, nn = tid & 63;
;       int np = n0 + nn;
;       int ns = kind == 0 ? win_src_col(np) : np;
;       tile[kk][nn] = ns >= 0 ? src[(long)(k0 + kk) * sld + ns] : 0.f;
;     }
;     __syncthreads();
; #pragma unroll 4
;     for (int i = 0; i < 16; ++i) {
;       int nn = (tid >> 6) + 4 * i, kk = tid & 63;
;       dst[((long)((k0 + kk) >> 5) * ntot + (n0 + nn)) * 32 + ((k0 + kk) & 31)] = f2bf(tile[kk][nn]);
;     }
;     __syncthreads();
;   }
.Lcv_noload:
	v_readlane_b32 s40, v242, 2
	s_cmp_eq_u32 s54, s40
	s_cbranch_scc1 .Lcv_first
	s_waitcnt lgkmcnt(0)
	s_barrier
	ds_read_b32 v18, v243
	ds_read_b32 v19, v243 offset:260
	ds_read_b32 v20, v243 offset:520
	ds_read_b32 v21, v243 offset:780
	ds_read_b32 v22, v243 offset:1040
	ds_read_b32 v23, v243 offset:1300
	ds_read_b32 v24, v243 offset:1560
	ds_read_b32 v25, v243 offset:1820
	ds_read_b32 v244, v243 offset:8320
	ds_read_b32 v245, v243 offset:8580
	ds_read_b32 v246, v243 offset:8840
	ds_read_b32 v247, v243 offset:9100
	ds_read_b32 v248, v243 offset:9360
	ds_read_b32 v249, v243 offset:9620
	ds_read_b32 v250, v243 offset:9880
	ds_read_b32 v251, v243 offset:10140
	s_waitcnt lgkmcnt(8)
	v_cvt_pk_bf16_f32 v18, v18, v19
	v_cvt_pk_bf16_f32 v19, v20, v21
	v_cvt_pk_bf16_f32 v20, v22, v23
	v_cvt_pk_bf16_f32 v21, v24, v25
	global_store_dwordx4 v252, v[18:21], s[12:13]
	s_waitcnt lgkmcnt(0)
	v_cvt_pk_bf16_f32 v244, v244, v245
	v_cvt_pk_bf16_f32 v245, v246, v247
	v_cvt_pk_bf16_f32 v246, v248, v249
	v_cvt_pk_bf16_f32 v247, v250, v251
	global_store_dwordx4 v252, v[244:247], s[100:101]
	v_xor_b32_e32 v243, 0x8000, v243
	s_cmp_lt_i32 s54, s99
	s_cbranch_scc0 .Lcv_done
	s_waitcnt vmcnt(2)
	s_branch .Lcv_write

; __device__ void ph_convert(const Params& p, int l, char* smem) {
;     ...
;   for (int t = blockIdx.x; t < 5152; t += gridDim.x) {
;     const float* src; long sld; u16* dst; int n0, k0, kind; long ntot = D;
;     if (t < 4128) { kind = 0; ntot = NPAD; n0 = (t / 16) * 64; k0 = (t % 16) * 64; src = p.w_in + (long)l * D * IN_DIM; sld = IN_DIM; dst = p.WinT; }
;     else if (t < 4896) { int u = t - 4128; int i = u / 256; u %= 256; kind = 1; n0 = (u / 16) * 64; k0 = (u % 16) * 64;
;       src = p.w_branch + ((long)l * 3 + i) * D * D; sld = D; dst = p.WbrT + (long)i * D * D; }
;     else { int u = t - 4896; kind = 1; n0 = (u / 16) * 64; k0 = (u % 16) * 64; src = p.w_out + (long)l * D * D; sld = D; dst = p.WoT; }
; #pragma unroll 4
;     for (int i = 0; i < 16; ++i) {
;       int kk = (tid >> 6) + 4 * i, nn = tid & 63;
;       int np = n0 + nn;
;       int ns = kind == 0 ? win_src_col(np) : np;
;       tile[kk][nn] = ns >= 0 ? src[(long)(k0 + kk) * sld + ns] : 0.f;
;     }
.Lcv_write:
	ds_write_b32 v26, v2
	ds_write_b32 v26, v3 offset:1040
	ds_write_b32 v26, v4 offset:2080
	ds_write_b32 v26, v5 offset:3120
	ds_write_b32 v26, v6 offset:4160
	ds_write_b32 v26, v7 offset:5200
	ds_write_b32 v26, v8 offset:6240
	ds_write_b32 v26, v9 offset:7280
	ds_write_b32 v26, v10 offset:8320
	ds_write_b32 v26, v11 offset:9360
	ds_write_b32 v26, v12 offset:10400
	ds_write_b32 v26, v13 offset:11440
	ds_write_b32 v26, v14 offset:12480
	ds_write_b32 v26, v15 offset:13520
	ds_write_b32 v26, v16 offset:14560
	ds_write_b32 v26, v17 offset:15600
	v_xor_b32_e32 v26, 0x8000, v26
	s_mov_b64 s[12:13], s[46:47]
	s_mov_b64 s[100:101], s[52:53]
	v_readlane_b32 s38, v242, 3
	s_add_i32 s54, s54, s38
	s_cmp_lt_i32 s54, s99
	s_cbranch_scc1 .Lcv_top
	s_cmp_lt_i32 s98, 0
	s_cbranch_scc1 .Lcv_top
	s_mov_b32 s54, s98
	s_add_u32 s99, s98, 1
	s_mov_b32 s98, -1
	s_branch .Lcv_top
